# v14 + GEMM loops: one LDS-DMA piece and one fragment ds_read per MFMA gap in phases P1-P3 (instead of 8 pieces back-to-back after the barrier)
# speedup vs baseline: 1.0103x; 1.0100x over previous
.Lgm_loop_B:
	ds_read_b128 v[112:115], v213 offset:0
	ds_read_b128 v[116:119], v213 offset:4096
	ds_read_b128 v[120:123], v217 offset:32768
	ds_read_b128 v[124:127], v217 offset:36864
	s_waitcnt lgkmcnt(12)
	v_mfma_f32_32x32x16_bf16 v[48:63], v[64:67], v[72:75], v[48:63]
	v_mfma_f32_32x32x16_bf16 v[32:47], v[64:67], v[76:79], v[32:47]
	v_mfma_f32_32x32x16_bf16 v[16:31], v[68:71], v[72:75], v[16:31]
	v_mfma_f32_32x32x16_bf16 v[0:15], v[68:71], v[76:79], v[0:15]
	s_waitcnt vmcnt(0) lgkmcnt(0)
	s_barrier
	s_cmp_lt_u32 s64, 30
	s_cbranch_scc0 .Lgm_nodma0_B
	ds_read_b128 v[64:67], v210 offset:16384
	s_add_u32 m0, s65, 0x0
	s_nop 0
	global_load_lds_dwordx4 v206, s[68:69]
	v_mfma_f32_32x32x16_bf16 v[48:63], v[80:83], v[88:91], v[48:63]
	ds_read_b128 v[68:71], v210 offset:20480
	s_add_u32 m0, s65, 0x1000
	s_nop 0
	global_load_lds_dwordx4 v207, s[68:69]
	v_mfma_f32_32x32x16_bf16 v[32:47], v[80:83], v[92:95], v[32:47]
	ds_read_b128 v[72:75], v214 offset:49152
	s_add_u32 m0, s65, 0x2000
	s_nop 0
	global_load_lds_dwordx4 v208, s[68:69]
	v_mfma_f32_32x32x16_bf16 v[16:31], v[84:87], v[88:91], v[16:31]
	ds_read_b128 v[76:79], v214 offset:53248
	s_add_u32 m0, s65, 0x3000
	s_nop 0
	global_load_lds_dwordx4 v209, s[68:69]
	v_mfma_f32_32x32x16_bf16 v[0:15], v[84:87], v[92:95], v[0:15]
	ds_read_b128 v[80:83], v211 offset:16384
	s_add_u32 m0, s65, 0x8000
	s_nop 0
	global_load_lds_dwordx4 v206, s[70:71]
	v_mfma_f32_32x32x16_bf16 v[48:63], v[96:99], v[104:107], v[48:63]
	ds_read_b128 v[84:87], v211 offset:20480
	s_add_u32 m0, s65, 0x9000
	s_nop 0
	global_load_lds_dwordx4 v207, s[70:71]
	v_mfma_f32_32x32x16_bf16 v[32:47], v[96:99], v[108:111], v[32:47]
	ds_read_b128 v[88:91], v215 offset:49152
	s_add_u32 m0, s65, 0xa000
	s_nop 0
	global_load_lds_dwordx4 v208, s[70:71]
	v_mfma_f32_32x32x16_bf16 v[16:31], v[100:103], v[104:107], v[16:31]
	ds_read_b128 v[92:95], v215 offset:53248
	s_add_u32 m0, s65, 0xb000
	s_nop 0
	global_load_lds_dwordx4 v209, s[70:71]
	v_mfma_f32_32x32x16_bf16 v[0:15], v[100:103], v[108:111], v[0:15]
	ds_read_b128 v[96:99], v212 offset:16384
	s_add_u32 s68, s68, 0x80
	s_addc_u32 s69, s69, 0
	s_add_u32 s70, s70, 0x80
	s_addc_u32 s71, s71, 0
	v_mfma_f32_32x32x16_bf16 v[48:63], v[112:115], v[120:123], v[48:63]
	ds_read_b128 v[100:103], v212 offset:20480
	v_mfma_f32_32x32x16_bf16 v[32:47], v[112:115], v[124:127], v[32:47]
	ds_read_b128 v[104:107], v216 offset:49152
	v_mfma_f32_32x32x16_bf16 v[16:31], v[116:119], v[120:123], v[16:31]
	ds_read_b128 v[108:111], v216 offset:53248
	v_mfma_f32_32x32x16_bf16 v[0:15], v[116:119], v[124:127], v[0:15]
	s_branch .Lgm_join0_B

.Lgm_join0_B:
	ds_read_b128 v[112:115], v213 offset:16384
	ds_read_b128 v[116:119], v213 offset:20480
	ds_read_b128 v[120:123], v217 offset:49152
	ds_read_b128 v[124:127], v217 offset:53248
	s_waitcnt lgkmcnt(12)
	v_mfma_f32_32x32x16_bf16 v[48:63], v[64:67], v[72:75], v[48:63]
	v_mfma_f32_32x32x16_bf16 v[32:47], v[64:67], v[76:79], v[32:47]
	v_mfma_f32_32x32x16_bf16 v[16:31], v[68:71], v[72:75], v[16:31]
	v_mfma_f32_32x32x16_bf16 v[0:15], v[68:71], v[76:79], v[0:15]
	s_waitcnt vmcnt(0) lgkmcnt(0)
	s_barrier
	s_cmp_lt_u32 s64, 30
	s_cbranch_scc0 .Lgm_nodma1_B
	ds_read_b128 v[64:67], v210 offset:0
	s_add_u32 m0, s65, 0x4000
	s_nop 0
	global_load_lds_dwordx4 v206, s[68:69]
	v_mfma_f32_32x32x16_bf16 v[48:63], v[80:83], v[88:91], v[48:63]
	ds_read_b128 v[68:71], v210 offset:4096
	s_add_u32 m0, s65, 0x5000
	s_nop 0
	global_load_lds_dwordx4 v207, s[68:69]
	v_mfma_f32_32x32x16_bf16 v[32:47], v[80:83], v[92:95], v[32:47]
	ds_read_b128 v[72:75], v214 offset:32768
	s_add_u32 m0, s65, 0x6000
	s_nop 0
	global_load_lds_dwordx4 v208, s[68:69]
	v_mfma_f32_32x32x16_bf16 v[16:31], v[84:87], v[88:91], v[16:31]
	ds_read_b128 v[76:79], v214 offset:36864
	s_add_u32 m0, s65, 0x7000
	s_nop 0
	global_load_lds_dwordx4 v209, s[68:69]
	v_mfma_f32_32x32x16_bf16 v[0:15], v[84:87], v[92:95], v[0:15]
	ds_read_b128 v[80:83], v211 offset:0
	s_add_u32 m0, s65, 0xc000
	s_nop 0
	global_load_lds_dwordx4 v206, s[70:71]
	v_mfma_f32_32x32x16_bf16 v[48:63], v[96:99], v[104:107], v[48:63]
	ds_read_b128 v[84:87], v211 offset:4096
	s_add_u32 m0, s65, 0xd000
	s_nop 0
	global_load_lds_dwordx4 v207, s[70:71]
	v_mfma_f32_32x32x16_bf16 v[32:47], v[96:99], v[108:111], v[32:47]
	ds_read_b128 v[88:91], v215 offset:32768
	s_add_u32 m0, s65, 0xe000
	s_nop 0
	global_load_lds_dwordx4 v208, s[70:71]
	v_mfma_f32_32x32x16_bf16 v[16:31], v[100:103], v[104:107], v[16:31]
	ds_read_b128 v[92:95], v215 offset:36864
	s_add_u32 m0, s65, 0xf000
	s_nop 0
	global_load_lds_dwordx4 v209, s[70:71]
	v_mfma_f32_32x32x16_bf16 v[0:15], v[100:103], v[108:111], v[0:15]
	ds_read_b128 v[96:99], v212 offset:0
	s_add_u32 s68, s68, 0x80
	s_addc_u32 s69, s69, 0
	s_add_u32 s70, s70, 0x80
	s_addc_u32 s71, s71, 0
	v_mfma_f32_32x32x16_bf16 v[48:63], v[112:115], v[120:123], v[48:63]
	ds_read_b128 v[100:103], v212 offset:4096
	v_mfma_f32_32x32x16_bf16 v[32:47], v[112:115], v[124:127], v[32:47]
	ds_read_b128 v[104:107], v216 offset:32768
	v_mfma_f32_32x32x16_bf16 v[16:31], v[116:119], v[120:123], v[16:31]
	ds_read_b128 v[108:111], v216 offset:36864
	v_mfma_f32_32x32x16_bf16 v[0:15], v[116:119], v[124:127], v[0:15]
	s_branch .Lgm_join1_B

.Lgm_loop_gemmF2:
	ds_read_b128 v[234:237], v148 offset:0
	ds_read_b128 v[238:241], v148 offset:4096
	ds_read_b128 v[242:245], v149 offset:32768
	ds_read_b128 v[246:249], v149 offset:36864
	s_waitcnt lgkmcnt(12)
	v_mfma_f32_32x32x16_bf16 v[32:47], v[186:189], v[194:197], v[32:47]
	v_mfma_f32_32x32x16_bf16 v[48:63], v[186:189], v[198:201], v[48:63]
	v_mfma_f32_32x32x16_bf16 v[0:15], v[190:193], v[194:197], v[0:15]
	v_mfma_f32_32x32x16_bf16 v[16:31], v[190:193], v[198:201], v[16:31]
	s_waitcnt vmcnt(0) lgkmcnt(0)
	s_barrier
	s_cmp_lt_u32 s60, 14
	s_cbranch_scc0 .Lgm_nodma0_gemmF2
	ds_read_b128 v[186:189], v142 offset:16384
	s_add_u32 m0, s61, 0x0
	s_nop 0
	global_load_lds_dwordx4 v64, s[56:57]
	v_mfma_f32_32x32x16_bf16 v[32:47], v[202:205], v[210:213], v[32:47]
	ds_read_b128 v[190:193], v142 offset:20480
	s_add_u32 m0, s61, 0x1000
	s_nop 0
	global_load_lds_dwordx4 v65, s[56:57]
	v_mfma_f32_32x32x16_bf16 v[48:63], v[202:205], v[214:217], v[48:63]
	ds_read_b128 v[194:197], v143 offset:49152
	s_add_u32 m0, s61, 0x2000
	s_nop 0
	global_load_lds_dwordx4 v66, s[56:57]
	v_mfma_f32_32x32x16_bf16 v[0:15], v[206:209], v[210:213], v[0:15]
	ds_read_b128 v[198:201], v143 offset:53248
	s_add_u32 m0, s61, 0x3000
	s_nop 0
	global_load_lds_dwordx4 v67, s[56:57]
	v_mfma_f32_32x32x16_bf16 v[16:31], v[206:209], v[214:217], v[16:31]
	ds_read_b128 v[202:205], v144 offset:16384
	s_add_u32 m0, s61, 0x8000
	s_nop 0
	global_load_lds_dwordx4 v64, s[58:59]
	v_mfma_f32_32x32x16_bf16 v[32:47], v[218:221], v[226:229], v[32:47]
	ds_read_b128 v[206:209], v144 offset:20480
	s_add_u32 m0, s61, 0x9000
	s_nop 0
	global_load_lds_dwordx4 v65, s[58:59]
	v_mfma_f32_32x32x16_bf16 v[48:63], v[218:221], v[230:233], v[48:63]
	ds_read_b128 v[210:213], v145 offset:49152
	s_add_u32 m0, s61, 0xa000
	s_nop 0
	global_load_lds_dwordx4 v66, s[58:59]
	v_mfma_f32_32x32x16_bf16 v[0:15], v[222:225], v[226:229], v[0:15]
	ds_read_b128 v[214:217], v145 offset:53248
	s_add_u32 m0, s61, 0xb000
	s_nop 0
	global_load_lds_dwordx4 v67, s[58:59]
	v_mfma_f32_32x32x16_bf16 v[16:31], v[222:225], v[230:233], v[16:31]
	ds_read_b128 v[218:221], v146 offset:16384
	s_add_u32 s56, s56, 0x80
	s_addc_u32 s57, s57, 0
	s_add_u32 s58, s58, 0x80
	s_addc_u32 s59, s59, 0
	v_mfma_f32_32x32x16_bf16 v[32:47], v[234:237], v[242:245], v[32:47]
	ds_read_b128 v[222:225], v146 offset:20480
	v_mfma_f32_32x32x16_bf16 v[48:63], v[234:237], v[246:249], v[48:63]
	ds_read_b128 v[226:229], v147 offset:49152
	v_mfma_f32_32x32x16_bf16 v[0:15], v[238:241], v[242:245], v[0:15]
	ds_read_b128 v[230:233], v147 offset:53248
	v_mfma_f32_32x32x16_bf16 v[16:31], v[238:241], v[246:249], v[16:31]
	s_branch .Lgm_join0_gemmF2

.Lgm_join0_gemmF2:
	ds_read_b128 v[234:237], v148 offset:16384
	ds_read_b128 v[238:241], v148 offset:20480
	ds_read_b128 v[242:245], v149 offset:49152
	ds_read_b128 v[246:249], v149 offset:53248
	s_waitcnt lgkmcnt(12)
	v_mfma_f32_32x32x16_bf16 v[32:47], v[186:189], v[194:197], v[32:47]
	v_mfma_f32_32x32x16_bf16 v[48:63], v[186:189], v[198:201], v[48:63]
	v_mfma_f32_32x32x16_bf16 v[0:15], v[190:193], v[194:197], v[0:15]
	v_mfma_f32_32x32x16_bf16 v[16:31], v[190:193], v[198:201], v[16:31]
	s_waitcnt vmcnt(0) lgkmcnt(0)
	s_barrier
	s_cmp_lt_u32 s60, 14
	s_cbranch_scc0 .Lgm_nodma1_gemmF2
	ds_read_b128 v[186:189], v142 offset:0
	s_add_u32 m0, s61, 0x4000
	s_nop 0
	global_load_lds_dwordx4 v64, s[56:57]
	v_mfma_f32_32x32x16_bf16 v[32:47], v[202:205], v[210:213], v[32:47]
	ds_read_b128 v[190:193], v142 offset:4096
	s_add_u32 m0, s61, 0x5000
	s_nop 0
	global_load_lds_dwordx4 v65, s[56:57]
	v_mfma_f32_32x32x16_bf16 v[48:63], v[202:205], v[214:217], v[48:63]
	ds_read_b128 v[194:197], v143 offset:32768
	s_add_u32 m0, s61, 0x6000
	s_nop 0
	global_load_lds_dwordx4 v66, s[56:57]
	v_mfma_f32_32x32x16_bf16 v[0:15], v[206:209], v[210:213], v[0:15]
	ds_read_b128 v[198:201], v143 offset:36864
	s_add_u32 m0, s61, 0x7000
	s_nop 0
	global_load_lds_dwordx4 v67, s[56:57]
	v_mfma_f32_32x32x16_bf16 v[16:31], v[206:209], v[214:217], v[16:31]
	ds_read_b128 v[202:205], v144 offset:0
	s_add_u32 m0, s61, 0xc000
	s_nop 0
	global_load_lds_dwordx4 v64, s[58:59]
	v_mfma_f32_32x32x16_bf16 v[32:47], v[218:221], v[226:229], v[32:47]
	ds_read_b128 v[206:209], v144 offset:4096
	s_add_u32 m0, s61, 0xd000
	s_nop 0
	global_load_lds_dwordx4 v65, s[58:59]
	v_mfma_f32_32x32x16_bf16 v[48:63], v[218:221], v[230:233], v[48:63]
	ds_read_b128 v[210:213], v145 offset:32768
	s_add_u32 m0, s61, 0xe000
	s_nop 0
	global_load_lds_dwordx4 v66, s[58:59]
	v_mfma_f32_32x32x16_bf16 v[0:15], v[222:225], v[226:229], v[0:15]
	ds_read_b128 v[214:217], v145 offset:36864
	s_add_u32 m0, s61, 0xf000
	s_nop 0
	global_load_lds_dwordx4 v67, s[58:59]
	v_mfma_f32_32x32x16_bf16 v[16:31], v[222:225], v[230:233], v[16:31]
	ds_read_b128 v[218:221], v146 offset:0
	s_add_u32 s56, s56, 0x80
	s_addc_u32 s57, s57, 0
	s_add_u32 s58, s58, 0x80
	s_addc_u32 s59, s59, 0
	v_mfma_f32_32x32x16_bf16 v[32:47], v[234:237], v[242:245], v[32:47]
	ds_read_b128 v[222:225], v146 offset:4096
	v_mfma_f32_32x32x16_bf16 v[48:63], v[234:237], v[246:249], v[48:63]
	ds_read_b128 v[226:229], v147 offset:32768
	v_mfma_f32_32x32x16_bf16 v[0:15], v[238:241], v[242:245], v[0:15]
	ds_read_b128 v[230:233], v147 offset:36864
	v_mfma_f32_32x32x16_bf16 v[16:31], v[238:241], v[246:249], v[16:31]
	s_branch .Lgm_join1_gemmF2

.Lgm_loop_G:
	ds_read_b128 v[112:115], v197 offset:0
	ds_read_b128 v[116:119], v197 offset:4096
	ds_read_b128 v[120:123], v201 offset:32768
	ds_read_b128 v[124:127], v201 offset:36864
	s_waitcnt lgkmcnt(12)
	v_mfma_f32_32x32x16_bf16 v[48:63], v[64:67], v[72:75], v[48:63]
	v_mfma_f32_32x32x16_bf16 v[32:47], v[64:67], v[76:79], v[32:47]
	v_mfma_f32_32x32x16_bf16 v[16:31], v[68:71], v[72:75], v[16:31]
	v_mfma_f32_32x32x16_bf16 v[0:15], v[68:71], v[76:79], v[0:15]
	s_waitcnt vmcnt(0) lgkmcnt(0)
	s_barrier
	s_cmp_lt_u32 s6, 30
	s_cbranch_scc0 .Lgm_nodma0_G
	ds_read_b128 v[64:67], v194 offset:16384
	s_add_u32 m0, s25, 0x0
	s_nop 0
	global_load_lds_dwordx4 v190, s[16:17]
	v_mfma_f32_32x32x16_bf16 v[48:63], v[80:83], v[88:91], v[48:63]
	ds_read_b128 v[68:71], v194 offset:20480
	s_add_u32 m0, s25, 0x1000
	s_nop 0
	global_load_lds_dwordx4 v191, s[16:17]
	v_mfma_f32_32x32x16_bf16 v[32:47], v[80:83], v[92:95], v[32:47]
	ds_read_b128 v[72:75], v198 offset:49152
	s_add_u32 m0, s25, 0x2000
	s_nop 0
	global_load_lds_dwordx4 v192, s[16:17]
	v_mfma_f32_32x32x16_bf16 v[16:31], v[84:87], v[88:91], v[16:31]
	ds_read_b128 v[76:79], v198 offset:53248
	s_add_u32 m0, s25, 0x3000
	s_nop 0
	global_load_lds_dwordx4 v193, s[16:17]
	v_mfma_f32_32x32x16_bf16 v[0:15], v[84:87], v[92:95], v[0:15]
	ds_read_b128 v[80:83], v195 offset:16384
	s_add_u32 m0, s25, 0x8000
	s_nop 0
	global_load_lds_dwordx4 v190, s[20:21]
	v_mfma_f32_32x32x16_bf16 v[48:63], v[96:99], v[104:107], v[48:63]
	ds_read_b128 v[84:87], v195 offset:20480
	s_add_u32 m0, s25, 0x9000
	s_nop 0
	global_load_lds_dwordx4 v191, s[20:21]
	v_mfma_f32_32x32x16_bf16 v[32:47], v[96:99], v[108:111], v[32:47]
	ds_read_b128 v[88:91], v199 offset:49152
	s_add_u32 m0, s25, 0xa000
	s_nop 0
	global_load_lds_dwordx4 v192, s[20:21]
	v_mfma_f32_32x32x16_bf16 v[16:31], v[100:103], v[104:107], v[16:31]
	ds_read_b128 v[92:95], v199 offset:53248
	s_add_u32 m0, s25, 0xb000
	s_nop 0
	global_load_lds_dwordx4 v193, s[20:21]
	v_mfma_f32_32x32x16_bf16 v[0:15], v[100:103], v[108:111], v[0:15]
	ds_read_b128 v[96:99], v196 offset:16384
	s_add_u32 s16, s16, 0x80
	s_addc_u32 s17, s17, 0
	s_add_u32 s20, s20, 0x80
	s_addc_u32 s21, s21, 0
	v_mfma_f32_32x32x16_bf16 v[48:63], v[112:115], v[120:123], v[48:63]
	ds_read_b128 v[100:103], v196 offset:20480
	v_mfma_f32_32x32x16_bf16 v[32:47], v[112:115], v[124:127], v[32:47]
	ds_read_b128 v[104:107], v200 offset:49152
	v_mfma_f32_32x32x16_bf16 v[16:31], v[116:119], v[120:123], v[16:31]
	ds_read_b128 v[108:111], v200 offset:53248
	v_mfma_f32_32x32x16_bf16 v[0:15], v[116:119], v[124:127], v[0:15]
	s_branch .Lgm_join0_G

.Lgm_join0_G:
	ds_read_b128 v[112:115], v197 offset:16384
	ds_read_b128 v[116:119], v197 offset:20480
	ds_read_b128 v[120:123], v201 offset:49152
	ds_read_b128 v[124:127], v201 offset:53248
	s_waitcnt lgkmcnt(12)
	v_mfma_f32_32x32x16_bf16 v[48:63], v[64:67], v[72:75], v[48:63]
	v_mfma_f32_32x32x16_bf16 v[32:47], v[64:67], v[76:79], v[32:47]
	v_mfma_f32_32x32x16_bf16 v[16:31], v[68:71], v[72:75], v[16:31]
	v_mfma_f32_32x32x16_bf16 v[0:15], v[68:71], v[76:79], v[0:15]
	s_waitcnt vmcnt(0) lgkmcnt(0)
	s_barrier
	s_cmp_lt_u32 s6, 30
	s_cbranch_scc0 .Lgm_nodma1_G
	ds_read_b128 v[64:67], v194 offset:0
	s_add_u32 m0, s25, 0x4000
	s_nop 0
	global_load_lds_dwordx4 v190, s[16:17]
	v_mfma_f32_32x32x16_bf16 v[48:63], v[80:83], v[88:91], v[48:63]
	ds_read_b128 v[68:71], v194 offset:4096
	s_add_u32 m0, s25, 0x5000
	s_nop 0
	global_load_lds_dwordx4 v191, s[16:17]
	v_mfma_f32_32x32x16_bf16 v[32:47], v[80:83], v[92:95], v[32:47]
	ds_read_b128 v[72:75], v198 offset:32768
	s_add_u32 m0, s25, 0x6000
	s_nop 0
	global_load_lds_dwordx4 v192, s[16:17]
	v_mfma_f32_32x32x16_bf16 v[16:31], v[84:87], v[88:91], v[16:31]
	ds_read_b128 v[76:79], v198 offset:36864
	s_add_u32 m0, s25, 0x7000
	s_nop 0
	global_load_lds_dwordx4 v193, s[16:17]
	v_mfma_f32_32x32x16_bf16 v[0:15], v[84:87], v[92:95], v[0:15]
	ds_read_b128 v[80:83], v195 offset:0
	s_add_u32 m0, s25, 0xc000
	s_nop 0
	global_load_lds_dwordx4 v190, s[20:21]
	v_mfma_f32_32x32x16_bf16 v[48:63], v[96:99], v[104:107], v[48:63]
	ds_read_b128 v[84:87], v195 offset:4096
	s_add_u32 m0, s25, 0xd000
	s_nop 0
	global_load_lds_dwordx4 v191, s[20:21]
	v_mfma_f32_32x32x16_bf16 v[32:47], v[96:99], v[108:111], v[32:47]
	ds_read_b128 v[88:91], v199 offset:32768
	s_add_u32 m0, s25, 0xe000
	s_nop 0
	global_load_lds_dwordx4 v192, s[20:21]
	v_mfma_f32_32x32x16_bf16 v[16:31], v[100:103], v[104:107], v[16:31]
	ds_read_b128 v[92:95], v199 offset:36864
	s_add_u32 m0, s25, 0xf000
	s_nop 0
	global_load_lds_dwordx4 v193, s[20:21]
	v_mfma_f32_32x32x16_bf16 v[0:15], v[100:103], v[108:111], v[0:15]
	ds_read_b128 v[96:99], v196 offset:0
	s_add_u32 s16, s16, 0x80
	s_addc_u32 s17, s17, 0
	s_add_u32 s20, s20, 0x80
	s_addc_u32 s21, s21, 0
	v_mfma_f32_32x32x16_bf16 v[48:63], v[112:115], v[120:123], v[48:63]
	ds_read_b128 v[100:103], v196 offset:4096
	v_mfma_f32_32x32x16_bf16 v[32:47], v[112:115], v[124:127], v[32:47]
	ds_read_b128 v[104:107], v200 offset:32768
	v_mfma_f32_32x32x16_bf16 v[16:31], v[116:119], v[120:123], v[16:31]
	ds_read_b128 v[108:111], v200 offset:36864
	v_mfma_f32_32x32x16_bf16 v[0:15], v[116:119], v[124:127], v[0:15]
	s_branch .Lgm_join1_G

.Lgm_loop_H:
	ds_read_b128 v[112:115], v185 offset:0
	ds_read_b128 v[116:119], v185 offset:4096
	ds_read_b128 v[120:123], v186 offset:32768
	ds_read_b128 v[124:127], v186 offset:36864
	s_waitcnt lgkmcnt(12)
	v_mfma_f32_32x32x16_bf16 v[48:63], v[64:67], v[72:75], v[48:63]
	v_mfma_f32_32x32x16_bf16 v[32:47], v[64:67], v[76:79], v[32:47]
	v_mfma_f32_32x32x16_bf16 v[16:31], v[68:71], v[72:75], v[16:31]
	v_mfma_f32_32x32x16_bf16 v[0:15], v[68:71], v[76:79], v[0:15]
	s_waitcnt vmcnt(0) lgkmcnt(0)
	s_barrier
	s_cmp_lt_u32 s12, 30
	s_cbranch_scc0 .Lgm_nodma0_H
	ds_read_b128 v[64:67], v177 offset:16384
	s_add_u32 m0, s36, 0x0
	s_nop 0
	global_load_lds_dwordx4 v188, s[16:17]
	v_mfma_f32_32x32x16_bf16 v[48:63], v[80:83], v[88:91], v[48:63]
	ds_read_b128 v[68:71], v177 offset:20480
	s_add_u32 m0, s36, 0x1000
	s_nop 0
	global_load_lds_dwordx4 v189, s[16:17]
	v_mfma_f32_32x32x16_bf16 v[32:47], v[80:83], v[92:95], v[32:47]
	ds_read_b128 v[72:75], v178 offset:49152
	s_add_u32 m0, s36, 0x2000
	s_nop 0
	global_load_lds_dwordx4 v190, s[16:17]
	v_mfma_f32_32x32x16_bf16 v[16:31], v[84:87], v[88:91], v[16:31]
	ds_read_b128 v[76:79], v178 offset:53248
	s_add_u32 m0, s36, 0x3000
	s_nop 0
	global_load_lds_dwordx4 v191, s[16:17]
	v_mfma_f32_32x32x16_bf16 v[0:15], v[84:87], v[92:95], v[0:15]
	ds_read_b128 v[80:83], v179 offset:16384
	s_add_u32 m0, s36, 0x8000
	s_nop 0
	global_load_lds_dwordx4 v188, s[34:35]
	v_mfma_f32_32x32x16_bf16 v[48:63], v[96:99], v[104:107], v[48:63]
	ds_read_b128 v[84:87], v179 offset:20480
	s_add_u32 m0, s36, 0x9000
	s_nop 0
	global_load_lds_dwordx4 v189, s[34:35]
	v_mfma_f32_32x32x16_bf16 v[32:47], v[96:99], v[108:111], v[32:47]
	ds_read_b128 v[88:91], v182 offset:49152
	s_add_u32 m0, s36, 0xa000
	s_nop 0
	global_load_lds_dwordx4 v190, s[34:35]
	v_mfma_f32_32x32x16_bf16 v[16:31], v[100:103], v[104:107], v[16:31]
	ds_read_b128 v[92:95], v182 offset:53248
	s_add_u32 m0, s36, 0xb000
	s_nop 0
	global_load_lds_dwordx4 v191, s[34:35]
	v_mfma_f32_32x32x16_bf16 v[0:15], v[100:103], v[108:111], v[0:15]
	ds_read_b128 v[96:99], v183 offset:16384
	s_add_u32 s16, s16, 0x80
	s_addc_u32 s17, s17, 0
	s_add_u32 s34, s34, 0x80
	s_addc_u32 s35, s35, 0
	v_mfma_f32_32x32x16_bf16 v[48:63], v[112:115], v[120:123], v[48:63]
	ds_read_b128 v[100:103], v183 offset:20480
	v_mfma_f32_32x32x16_bf16 v[32:47], v[112:115], v[124:127], v[32:47]
	ds_read_b128 v[104:107], v184 offset:49152
	v_mfma_f32_32x32x16_bf16 v[16:31], v[116:119], v[120:123], v[16:31]
	ds_read_b128 v[108:111], v184 offset:53248
	v_mfma_f32_32x32x16_bf16 v[0:15], v[116:119], v[124:127], v[0:15]
	s_branch .Lgm_join0_H

.Lgm_join0_H:
	ds_read_b128 v[112:115], v185 offset:16384
	ds_read_b128 v[116:119], v185 offset:20480
	ds_read_b128 v[120:123], v186 offset:49152
	ds_read_b128 v[124:127], v186 offset:53248
	s_waitcnt lgkmcnt(12)
	v_mfma_f32_32x32x16_bf16 v[48:63], v[64:67], v[72:75], v[48:63]
	v_mfma_f32_32x32x16_bf16 v[32:47], v[64:67], v[76:79], v[32:47]
	v_mfma_f32_32x32x16_bf16 v[16:31], v[68:71], v[72:75], v[16:31]
	v_mfma_f32_32x32x16_bf16 v[0:15], v[68:71], v[76:79], v[0:15]
	s_waitcnt vmcnt(0) lgkmcnt(0)
	s_barrier
	s_cmp_lt_u32 s12, 30
	s_cbranch_scc0 .Lgm_nodma1_H
	ds_read_b128 v[64:67], v177 offset:0
	s_add_u32 m0, s36, 0x4000
	s_nop 0
	global_load_lds_dwordx4 v188, s[16:17]
	v_mfma_f32_32x32x16_bf16 v[48:63], v[80:83], v[88:91], v[48:63]
	ds_read_b128 v[68:71], v177 offset:4096
	s_add_u32 m0, s36, 0x5000
	s_nop 0
	global_load_lds_dwordx4 v189, s[16:17]
	v_mfma_f32_32x32x16_bf16 v[32:47], v[80:83], v[92:95], v[32:47]
	ds_read_b128 v[72:75], v178 offset:32768
	s_add_u32 m0, s36, 0x6000
	s_nop 0
	global_load_lds_dwordx4 v190, s[16:17]
	v_mfma_f32_32x32x16_bf16 v[16:31], v[84:87], v[88:91], v[16:31]
	ds_read_b128 v[76:79], v178 offset:36864
	s_add_u32 m0, s36, 0x7000
	s_nop 0
	global_load_lds_dwordx4 v191, s[16:17]
	v_mfma_f32_32x32x16_bf16 v[0:15], v[84:87], v[92:95], v[0:15]
	ds_read_b128 v[80:83], v179 offset:0
	s_add_u32 m0, s36, 0xc000
	s_nop 0
	global_load_lds_dwordx4 v188, s[34:35]
	v_mfma_f32_32x32x16_bf16 v[48:63], v[96:99], v[104:107], v[48:63]
	ds_read_b128 v[84:87], v179 offset:4096
	s_add_u32 m0, s36, 0xd000
	s_nop 0
	global_load_lds_dwordx4 v189, s[34:35]
	v_mfma_f32_32x32x16_bf16 v[32:47], v[96:99], v[108:111], v[32:47]
	ds_read_b128 v[88:91], v182 offset:32768
	s_add_u32 m0, s36, 0xe000
	s_nop 0
	global_load_lds_dwordx4 v190, s[34:35]
	v_mfma_f32_32x32x16_bf16 v[16:31], v[100:103], v[104:107], v[16:31]
	ds_read_b128 v[92:95], v182 offset:36864
	s_add_u32 m0, s36, 0xf000
	s_nop 0
	global_load_lds_dwordx4 v191, s[34:35]
	v_mfma_f32_32x32x16_bf16 v[0:15], v[100:103], v[108:111], v[0:15]
	ds_read_b128 v[96:99], v183 offset:0
	s_add_u32 s16, s16, 0x80
	s_addc_u32 s17, s17, 0
	s_add_u32 s34, s34, 0x80
	s_addc_u32 s35, s35, 0
	v_mfma_f32_32x32x16_bf16 v[48:63], v[112:115], v[120:123], v[48:63]
	ds_read_b128 v[100:103], v183 offset:4096
	v_mfma_f32_32x32x16_bf16 v[32:47], v[112:115], v[124:127], v[32:47]
	ds_read_b128 v[104:107], v184 offset:32768
	v_mfma_f32_32x32x16_bf16 v[16:31], v[116:119], v[120:123], v[16:31]
	ds_read_b128 v[108:111], v184 offset:36864
	v_mfma_f32_32x32x16_bf16 v[0:15], v[116:119], v[124:127], v[0:15]
	s_branch .Lgm_join1_H
